# attention loops: wave-mask negation moved from VALU (v_cndmask + v_cmp_ne) to one s_andn2_b64 with exec, 12 sites
# baseline (speedup 1.0000x reference)
.LBB0_1096:
	s_nop 1
	v_max_f32_e32 v66, v34, v35
	s_nop 1
	v_max_f32_e32 v67, v36, v37
	s_and_b64 vcc, exec, s[38:39]
	v_max3_f32 v33, v33, v66, v67
	s_cbranch_vccnz .LBB0_1100
	s_nop 1
	v_max_f32_e32 v66, v54, v55
	s_nop 1
	v_max_f32_e32 v67, v56, v57
	v_max3_f32 v33, v33, v66, v67
	s_nop 0
	s_andn2_b64 s[40:41], exec, s[10:11]
	s_andn2_b64 vcc, exec, s[10:11]
	s_cbranch_vccz .LBB0_1101

.LBB0_1100:
	s_nop 0
	s_andn2_b64 s[40:41], exec, s[10:11]
	s_andn2_b64 vcc, exec, s[10:11]
	s_cbranch_vccnz .LBB0_1098

.LBB0_1106:
	v_cmp_lt_i32_e32 vcc, v222, v221
	s_nop 0
	s_andn2_b64 s[42:43], exec, s[44:45]
	v_cndmask_b32_e32 v66, v220, v222, vcc
	v_lshlrev_b32_e32 v66, 2, v66
	ds_bpermute_b32 v66, v66, v33
	s_andn2_b64 vcc, exec, s[44:45]
	s_mov_b64 s[10:11], -1
	s_cbranch_vccnz .LBB0_1108
	s_mov_b64 s[10:11], 0

.LBB0_1115:
	s_nop 0
	s_andn2_b64 s[44:45], exec, s[16:17]
	s_andn2_b64 vcc, exec, s[16:17]
	s_mov_b64 s[10:11], -1
	s_cbranch_vccnz .LBB0_1117
	s_mov_b64 s[10:11], 0
